# nt (non-temporal) hint on in-proj and up-proj GEMM epilogue stores
# baseline (speedup 1.0000x reference)
; __device__ __forceinline__ unsigned pkh(float lo, float hi) { f32v2_t v; v.x = lo; v.y = hi; return __builtin_bit_cast(unsigned, __builtin_convertvector(v, bf16v2_t)); }
; __device__ __forceinline__ float bf_lo(unsigned w) { return __uint_as_float(w << 16); }
; __device__ __forceinline__ float bf_hi(unsigned w) { return __uint_as_float(w & 0xffff0000u); }
; __device__ __forceinline__ float sigmoidf_(float x) { return 1.0f / (1.0f + __expf(-x)); }
;     template <int MODE> __device__ __forceinline__ void run(const pg8::f32x4 (&acc)[2][2][4][2], const pg8::Unit& u, int wr, int wc, int fr, int fq) const {
;     ...
;                 for (int q = 0; q < 4; ++q) { const int m = 2 * mp + (q >> 1), bj = q & 1; const int row = u.pm * 256 + ai * 128 + wr * 64 + m * 16 + fr, col = u.pn * 256 + bj * 128 + wc * 32 + 8 * fq;
;                     const pg8::f32x4 t0 = acc[ai][bj][m][0], t1 = acc[ai][bj][m][1];
;                     float v[8] = {t0[0], t0[1], t0[2], t0[3], t1[0], t1[1], t1[2], t1[3]};
;                     if constexpr (MODE == 5) {
; #pragma unroll
;                         for (int e = 0; e < 8; ++e) { const float r = fmaxf(v[e], 0.f); v[e] = r * r; }
;                     }
;                     if constexpr (MODE == 6) { const u32x4 g = gpre[q];
;                         v[0] *= sigmoidf_(bf_lo(g.x)); v[1] *= sigmoidf_(bf_hi(g.x)); v[2] *= sigmoidf_(bf_lo(g.y)); v[3] *= sigmoidf_(bf_hi(g.y));
;                         v[4] *= sigmoidf_(bf_lo(g.z)); v[5] *= sigmoidf_(bf_hi(g.z)); v[6] *= sigmoidf_(bf_lo(g.w)); v[7] *= sigmoidf_(bf_hi(g.w)); }
;                     u32x4 w; w.x = pkh(v[0], v[1]); w.y = pkh(v[2], v[3]); w.z = pkh(v[4], v[5]); w.w = pkh(v[6], v[7]);
;                     *(u32x4*)(ob + (size_t)row * LDC + col) = w; }
.LBB0_60:
	s_mov_b64 s[34:35], -1
	s_mov_b64 s[28:29], 0
	s_cmp_lt_i32 s38, 4
	s_mov_b64 s[30:31], 0
	s_cbranch_scc1 .LBB0_71
	s_cmp_gt_i32 s38, 4
	s_cbranch_scc0 .LBB0_65
	s_cmp_eq_u32 s38, 5
	s_mov_b64 s[30:31], -1
	s_cbranch_scc0 .LBB0_64
	v_max_f32_e32 v2, v116, v116
	v_max_f32_e32 v3, v117, v117
	v_max_f32_e32 v2, 0, v2
	v_max_f32_e32 v3, 0, v3
	v_pk_mul_f32 v[132:133], v[2:3], v[2:3]
	v_max_f32_e32 v2, v118, v118
	v_max_f32_e32 v3, v119, v119
	v_max_f32_e32 v2, 0, v2
	v_max_f32_e32 v3, 0, v3
	v_pk_mul_f32 v[136:137], v[2:3], v[2:3]
	v_max_f32_e32 v2, v120, v120
	v_max_f32_e32 v3, v121, v121
	v_mov_b32_e32 v0, v210
	v_max_f32_e32 v2, 0, v2
	v_max_f32_e32 v3, 0, v3
	v_pk_mul_f32 v[138:139], v[2:3], v[2:3]
	v_max_f32_e32 v2, v122, v122
	v_max_f32_e32 v3, v123, v123
	v_and_or_b32 v134, v0, 15, s49
	v_lshrrev_b32_e32 v0, 1, v0
	s_lshl_b32 s2, s53, 8
	v_max_f32_e32 v2, 0, v2
	v_max_f32_e32 v3, 0, v3
	v_pk_mul_f32 v[140:141], v[2:3], v[2:3]
	v_lshl_add_u32 v2, s54, 8, v134
	v_and_or_b32 v0, v0, 24, s2
	v_or_b32_e32 v142, s50, v0
	v_ashrrev_i32_e32 v3, 31, v2
	v_cvt_pk_bf16_f32 v134, v132, v133
	v_lshlrev_b64 v[132:133], 14, v[2:3]
	v_ashrrev_i32_e32 v143, 31, v142
	v_cvt_pk_bf16_f32 v135, v136, v137
	v_cvt_pk_bf16_f32 v136, v138, v139
	v_lshl_add_u64 v[138:139], s[10:11], 0, v[132:133]
	v_lshlrev_b64 v[132:133], 1, v[142:143]
	v_cvt_pk_bf16_f32 v137, v140, v141
	v_lshl_add_u64 v[138:139], v[138:139], 0, v[132:133]
	v_max_f32_e32 v0, v124, v124
	global_store_dwordx4 v[138:139], v[134:137], off nt
	s_mov_b64 s[30:31], 0
	s_nop 0
	v_max_f32_e32 v134, 0, v0
	v_max_f32_e32 v0, v125, v125
	v_max_f32_e32 v135, 0, v0
	v_max_f32_e32 v0, v126, v126
	v_max_f32_e32 v136, 0, v0
	v_max_f32_e32 v0, v127, v127
	v_max_f32_e32 v137, 0, v0
	v_max_f32_e32 v0, v128, v128
	v_max_f32_e32 v140, 0, v0
	v_max_f32_e32 v0, v129, v129
	v_max_f32_e32 v141, 0, v0
	v_max_f32_e32 v0, v130, v130
	v_max_f32_e32 v142, 0, v0
	v_max_f32_e32 v0, v131, v131
	v_max_f32_e32 v143, 0, v0
	v_pk_mul_f32 v[134:135], v[134:135], v[134:135]
	v_pk_mul_f32 v[136:137], v[136:137], v[136:137]
	v_pk_mul_f32 v[140:141], v[140:141], v[140:141]
	v_pk_mul_f32 v[142:143], v[142:143], v[142:143]
	v_cvt_pk_bf16_f32 v134, v134, v135
	v_cvt_pk_bf16_f32 v135, v136, v137
	v_cvt_pk_bf16_f32 v136, v140, v141
	v_cvt_pk_bf16_f32 v137, v142, v143
	v_max_f32_e32 v0, v100, v100
	global_store_dwordx4 v[138:139], v[134:137], off offset:256 nt
	v_or_b32_e32 v142, 16, v2
	v_ashrrev_i32_e32 v143, 31, v142
	v_max_f32_e32 v134, 0, v0
	v_max_f32_e32 v0, v101, v101
	v_max_f32_e32 v135, 0, v0
	v_max_f32_e32 v0, v102, v102
	v_max_f32_e32 v136, 0, v0
	v_max_f32_e32 v0, v103, v103
	v_max_f32_e32 v137, 0, v0
	v_max_f32_e32 v0, v104, v104
	v_max_f32_e32 v138, 0, v0
	v_max_f32_e32 v0, v105, v105
	v_max_f32_e32 v139, 0, v0
	v_max_f32_e32 v0, v106, v106
	v_pk_mul_f32 v[134:135], v[134:135], v[134:135]
	v_pk_mul_f32 v[136:137], v[136:137], v[136:137]
	v_pk_mul_f32 v[138:139], v[138:139], v[138:139]
	v_max_f32_e32 v140, 0, v0
	v_max_f32_e32 v0, v107, v107
	v_max_f32_e32 v141, 0, v0
	v_cvt_pk_bf16_f32 v134, v134, v135
	v_cvt_pk_bf16_f32 v135, v136, v137
	v_cvt_pk_bf16_f32 v136, v138, v139
	v_lshlrev_b64 v[138:139], 14, v[142:143]
	v_pk_mul_f32 v[140:141], v[140:141], v[140:141]
	v_lshl_add_u64 v[138:139], s[10:11], 0, v[138:139]
	v_cvt_pk_bf16_f32 v137, v140, v141
	v_lshl_add_u64 v[138:139], v[138:139], 0, v[132:133]
	v_max_f32_e32 v0, v108, v108
	global_store_dwordx4 v[138:139], v[134:137], off nt
	s_nop 1
	v_max_f32_e32 v134, 0, v0
	v_max_f32_e32 v0, v109, v109
	v_max_f32_e32 v135, 0, v0
	v_max_f32_e32 v0, v110, v110
	v_max_f32_e32 v136, 0, v0
	v_max_f32_e32 v0, v111, v111
	v_max_f32_e32 v137, 0, v0
	v_max_f32_e32 v0, v112, v112
	v_max_f32_e32 v140, 0, v0
	v_max_f32_e32 v0, v113, v113
	v_max_f32_e32 v141, 0, v0
	v_max_f32_e32 v0, v114, v114
	v_max_f32_e32 v142, 0, v0
	v_max_f32_e32 v0, v115, v115
	v_max_f32_e32 v143, 0, v0
	v_pk_mul_f32 v[134:135], v[134:135], v[134:135]
	v_pk_mul_f32 v[136:137], v[136:137], v[136:137]
	v_pk_mul_f32 v[140:141], v[140:141], v[140:141]
	v_pk_mul_f32 v[142:143], v[142:143], v[142:143]
	v_cvt_pk_bf16_f32 v134, v134, v135
	v_cvt_pk_bf16_f32 v135, v136, v137
	v_cvt_pk_bf16_f32 v136, v140, v141
	v_cvt_pk_bf16_f32 v137, v142, v143
	v_max_f32_e32 v0, v76, v76
	global_store_dwordx4 v[138:139], v[134:137], off offset:256 nt
	v_or_b32_e32 v142, 32, v2
	v_ashrrev_i32_e32 v143, 31, v142
	v_max_f32_e32 v134, 0, v0
	v_max_f32_e32 v0, v77, v77
	v_max_f32_e32 v135, 0, v0
	v_max_f32_e32 v0, v78, v78
	v_max_f32_e32 v136, 0, v0
	v_max_f32_e32 v0, v79, v79
	v_max_f32_e32 v137, 0, v0
	v_max_f32_e32 v0, v80, v80
	v_max_f32_e32 v138, 0, v0
	v_max_f32_e32 v0, v81, v81
	v_max_f32_e32 v139, 0, v0
	v_max_f32_e32 v0, v82, v82
	v_pk_mul_f32 v[134:135], v[134:135], v[134:135]
	v_pk_mul_f32 v[136:137], v[136:137], v[136:137]
	v_pk_mul_f32 v[138:139], v[138:139], v[138:139]
	v_max_f32_e32 v140, 0, v0
	v_max_f32_e32 v0, v83, v83
	v_max_f32_e32 v141, 0, v0
	v_cvt_pk_bf16_f32 v134, v134, v135
	v_cvt_pk_bf16_f32 v135, v136, v137
	v_cvt_pk_bf16_f32 v136, v138, v139
	v_lshlrev_b64 v[138:139], 14, v[142:143]
	v_pk_mul_f32 v[140:141], v[140:141], v[140:141]
	v_lshl_add_u64 v[138:139], s[10:11], 0, v[138:139]
	v_cvt_pk_bf16_f32 v137, v140, v141
	v_lshl_add_u64 v[138:139], v[138:139], 0, v[132:133]
	v_max_f32_e32 v0, v92, v92
	global_store_dwordx4 v[138:139], v[134:137], off nt
	s_nop 1
	v_max_f32_e32 v134, 0, v0
	v_max_f32_e32 v0, v93, v93
	v_max_f32_e32 v135, 0, v0
	v_max_f32_e32 v0, v94, v94
	v_max_f32_e32 v136, 0, v0
	v_max_f32_e32 v0, v95, v95
	v_max_f32_e32 v137, 0, v0
	v_max_f32_e32 v0, v96, v96
	v_max_f32_e32 v140, 0, v0
; __device__ __forceinline__ unsigned pkh(float lo, float hi) { f32v2_t v; v.x = lo; v.y = hi; return __builtin_bit_cast(unsigned, __builtin_convertvector(v, bf16v2_t)); }
; __device__ __forceinline__ float bf_lo(unsigned w) { return __uint_as_float(w << 16); }
; __device__ __forceinline__ float bf_hi(unsigned w) { return __uint_as_float(w & 0xffff0000u); }
; __device__ __forceinline__ float sigmoidf_(float x) { return 1.0f / (1.0f + __expf(-x)); }
;     template <int MODE> __device__ __forceinline__ void run(const pg8::f32x4 (&acc)[2][2][4][2], const pg8::Unit& u, int wr, int wc, int fr, int fq) const {
;     ...
;                 for (int q = 0; q < 4; ++q) { const int m = 2 * mp + (q >> 1), bj = q & 1; const int row = u.pm * 256 + ai * 128 + wr * 64 + m * 16 + fr, col = u.pn * 256 + bj * 128 + wc * 32 + 8 * fq;
;                     const pg8::f32x4 t0 = acc[ai][bj][m][0], t1 = acc[ai][bj][m][1];
;                     float v[8] = {t0[0], t0[1], t0[2], t0[3], t1[0], t1[1], t1[2], t1[3]};
;                     if constexpr (MODE == 5) {
; #pragma unroll
;                         for (int e = 0; e < 8; ++e) { const float r = fmaxf(v[e], 0.f); v[e] = r * r; }
;                     }
;                     if constexpr (MODE == 6) { const u32x4 g = gpre[q];
;                         v[0] *= sigmoidf_(bf_lo(g.x)); v[1] *= sigmoidf_(bf_hi(g.x)); v[2] *= sigmoidf_(bf_lo(g.y)); v[3] *= sigmoidf_(bf_hi(g.y));
;                         v[4] *= sigmoidf_(bf_lo(g.z)); v[5] *= sigmoidf_(bf_hi(g.z)); v[6] *= sigmoidf_(bf_lo(g.w)); v[7] *= sigmoidf_(bf_hi(g.w)); }
;                     u32x4 w; w.x = pkh(v[0], v[1]); w.y = pkh(v[2], v[3]); w.z = pkh(v[4], v[5]); w.w = pkh(v[6], v[7]);
;                     *(u32x4*)(ob + (size_t)row * LDC + col) = w; }
	v_max_f32_e32 v0, v97, v97
	v_max_f32_e32 v141, 0, v0
	v_max_f32_e32 v0, v98, v98
	v_max_f32_e32 v142, 0, v0
	v_max_f32_e32 v0, v99, v99
	v_max_f32_e32 v143, 0, v0
	v_pk_mul_f32 v[134:135], v[134:135], v[134:135]
	v_pk_mul_f32 v[136:137], v[136:137], v[136:137]
	v_pk_mul_f32 v[140:141], v[140:141], v[140:141]
	v_pk_mul_f32 v[142:143], v[142:143], v[142:143]
	v_cvt_pk_bf16_f32 v134, v134, v135
	v_cvt_pk_bf16_f32 v135, v136, v137
	v_cvt_pk_bf16_f32 v136, v140, v141
	v_cvt_pk_bf16_f32 v137, v142, v143
	v_max_f32_e32 v0, v44, v44
	global_store_dwordx4 v[138:139], v[134:137], off offset:256 nt
	v_or_b32_e32 v142, 48, v2
	v_ashrrev_i32_e32 v143, 31, v142
	v_max_f32_e32 v134, 0, v0
	v_max_f32_e32 v0, v45, v45
	v_max_f32_e32 v135, 0, v0
	v_max_f32_e32 v0, v46, v46
	v_max_f32_e32 v136, 0, v0
	v_max_f32_e32 v0, v47, v47
	v_max_f32_e32 v137, 0, v0
	v_max_f32_e32 v0, v48, v48
	v_max_f32_e32 v138, 0, v0
	v_max_f32_e32 v0, v49, v49
	v_max_f32_e32 v139, 0, v0
	v_max_f32_e32 v0, v50, v50
	v_pk_mul_f32 v[134:135], v[134:135], v[134:135]
	v_pk_mul_f32 v[136:137], v[136:137], v[136:137]
	v_pk_mul_f32 v[138:139], v[138:139], v[138:139]
	v_max_f32_e32 v140, 0, v0
	v_max_f32_e32 v0, v51, v51
	v_max_f32_e32 v141, 0, v0
	v_cvt_pk_bf16_f32 v134, v134, v135
	v_cvt_pk_bf16_f32 v135, v136, v137
	v_cvt_pk_bf16_f32 v136, v138, v139
	v_lshlrev_b64 v[138:139], 14, v[142:143]
	v_pk_mul_f32 v[140:141], v[140:141], v[140:141]
	v_lshl_add_u64 v[138:139], s[10:11], 0, v[138:139]
	v_cvt_pk_bf16_f32 v137, v140, v141
	v_lshl_add_u64 v[138:139], v[138:139], 0, v[132:133]
	v_max_f32_e32 v0, v68, v68
	global_store_dwordx4 v[138:139], v[134:137], off nt
	s_nop 1
	v_max_f32_e32 v134, 0, v0
	v_max_f32_e32 v0, v69, v69
	v_max_f32_e32 v135, 0, v0
	v_max_f32_e32 v0, v70, v70
	v_max_f32_e32 v136, 0, v0
	v_max_f32_e32 v0, v71, v71
	v_max_f32_e32 v137, 0, v0
	v_max_f32_e32 v0, v72, v72
	v_max_f32_e32 v140, 0, v0
	v_max_f32_e32 v0, v73, v73
	v_max_f32_e32 v141, 0, v0
	v_max_f32_e32 v0, v74, v74
	v_max_f32_e32 v142, 0, v0
	v_max_f32_e32 v0, v75, v75
	v_max_f32_e32 v143, 0, v0
	v_pk_mul_f32 v[134:135], v[134:135], v[134:135]
	v_pk_mul_f32 v[136:137], v[136:137], v[136:137]
	v_pk_mul_f32 v[140:141], v[140:141], v[140:141]
	v_pk_mul_f32 v[142:143], v[142:143], v[142:143]
	v_cvt_pk_bf16_f32 v134, v134, v135
	v_cvt_pk_bf16_f32 v135, v136, v137
	v_cvt_pk_bf16_f32 v136, v140, v141
	v_cvt_pk_bf16_f32 v137, v142, v143
	v_max_f32_e32 v0, v60, v60
	global_store_dwordx4 v[138:139], v[134:137], off offset:256 nt
	v_add_u32_e32 v142, 0x80, v2
	v_ashrrev_i32_e32 v143, 31, v142
	v_max_f32_e32 v134, 0, v0
	v_max_f32_e32 v0, v61, v61
	v_max_f32_e32 v135, 0, v0
	v_max_f32_e32 v0, v62, v62
	v_max_f32_e32 v136, 0, v0
	v_max_f32_e32 v0, v63, v63
	v_max_f32_e32 v137, 0, v0
	v_max_f32_e32 v0, v64, v64
	v_max_f32_e32 v138, 0, v0
	v_max_f32_e32 v0, v65, v65
	v_max_f32_e32 v139, 0, v0
	v_max_f32_e32 v0, v66, v66
	v_pk_mul_f32 v[134:135], v[134:135], v[134:135]
	v_pk_mul_f32 v[136:137], v[136:137], v[136:137]
	v_pk_mul_f32 v[138:139], v[138:139], v[138:139]
	v_max_f32_e32 v140, 0, v0
	v_max_f32_e32 v0, v67, v67
	v_max_f32_e32 v141, 0, v0
	v_cvt_pk_bf16_f32 v134, v134, v135
	v_cvt_pk_bf16_f32 v135, v136, v137
	v_cvt_pk_bf16_f32 v136, v138, v139
	v_lshlrev_b64 v[138:139], 14, v[142:143]
	v_pk_mul_f32 v[140:141], v[140:141], v[140:141]
	v_lshl_add_u64 v[138:139], s[10:11], 0, v[138:139]
	v_cvt_pk_bf16_f32 v137, v140, v141
	v_lshl_add_u64 v[138:139], v[138:139], 0, v[132:133]
	v_max_f32_e32 v0, v84, v84
	global_store_dwordx4 v[138:139], v[134:137], off nt
	s_nop 1
	v_max_f32_e32 v134, 0, v0
	v_max_f32_e32 v0, v85, v85
	v_max_f32_e32 v135, 0, v0
	v_max_f32_e32 v0, v86, v86
	v_max_f32_e32 v136, 0, v0
	v_max_f32_e32 v0, v87, v87
	v_max_f32_e32 v137, 0, v0
	v_max_f32_e32 v0, v88, v88
	v_max_f32_e32 v140, 0, v0
	v_max_f32_e32 v0, v89, v89
	v_max_f32_e32 v141, 0, v0
	v_max_f32_e32 v0, v90, v90
	v_max_f32_e32 v142, 0, v0
	v_max_f32_e32 v0, v91, v91
	v_max_f32_e32 v143, 0, v0
	v_pk_mul_f32 v[134:135], v[134:135], v[134:135]
	v_pk_mul_f32 v[136:137], v[136:137], v[136:137]
	v_pk_mul_f32 v[140:141], v[140:141], v[140:141]
	v_pk_mul_f32 v[142:143], v[142:143], v[142:143]
	v_cvt_pk_bf16_f32 v134, v134, v135
	v_cvt_pk_bf16_f32 v135, v136, v137
	v_cvt_pk_bf16_f32 v136, v140, v141
	v_cvt_pk_bf16_f32 v137, v142, v143
	v_max_f32_e32 v0, v36, v36
	global_store_dwordx4 v[138:139], v[134:137], off offset:256 nt
	v_add_u32_e32 v142, 0x90, v2
	v_ashrrev_i32_e32 v143, 31, v142
	v_max_f32_e32 v134, 0, v0
	v_max_f32_e32 v0, v37, v37
	v_max_f32_e32 v135, 0, v0
	v_max_f32_e32 v0, v38, v38
	v_max_f32_e32 v136, 0, v0
	v_max_f32_e32 v0, v39, v39
	v_max_f32_e32 v137, 0, v0
	v_max_f32_e32 v0, v40, v40
	v_max_f32_e32 v138, 0, v0
	v_max_f32_e32 v0, v41, v41
	v_max_f32_e32 v139, 0, v0
	v_max_f32_e32 v0, v42, v42
	v_pk_mul_f32 v[134:135], v[134:135], v[134:135]
	v_pk_mul_f32 v[136:137], v[136:137], v[136:137]
	v_pk_mul_f32 v[138:139], v[138:139], v[138:139]
	v_max_f32_e32 v140, 0, v0
	v_max_f32_e32 v0, v43, v43
; __device__ __forceinline__ unsigned pkh(float lo, float hi) { f32v2_t v; v.x = lo; v.y = hi; return __builtin_bit_cast(unsigned, __builtin_convertvector(v, bf16v2_t)); }
; __device__ __forceinline__ float bf_lo(unsigned w) { return __uint_as_float(w << 16); }
; __device__ __forceinline__ float bf_hi(unsigned w) { return __uint_as_float(w & 0xffff0000u); }
; __device__ __forceinline__ float sigmoidf_(float x) { return 1.0f / (1.0f + __expf(-x)); }
;     template <int MODE> __device__ __forceinline__ void run(const pg8::f32x4 (&acc)[2][2][4][2], const pg8::Unit& u, int wr, int wc, int fr, int fq) const {
;     ...
;                 for (int q = 0; q < 4; ++q) { const int m = 2 * mp + (q >> 1), bj = q & 1; const int row = u.pm * 256 + ai * 128 + wr * 64 + m * 16 + fr, col = u.pn * 256 + bj * 128 + wc * 32 + 8 * fq;
;                     const pg8::f32x4 t0 = acc[ai][bj][m][0], t1 = acc[ai][bj][m][1];
;                     float v[8] = {t0[0], t0[1], t0[2], t0[3], t1[0], t1[1], t1[2], t1[3]};
;                     if constexpr (MODE == 5) {
; #pragma unroll
;                         for (int e = 0; e < 8; ++e) { const float r = fmaxf(v[e], 0.f); v[e] = r * r; }
;                     }
;                     if constexpr (MODE == 6) { const u32x4 g = gpre[q];
;                         v[0] *= sigmoidf_(bf_lo(g.x)); v[1] *= sigmoidf_(bf_hi(g.x)); v[2] *= sigmoidf_(bf_lo(g.y)); v[3] *= sigmoidf_(bf_hi(g.y));
;                         v[4] *= sigmoidf_(bf_lo(g.z)); v[5] *= sigmoidf_(bf_hi(g.z)); v[6] *= sigmoidf_(bf_lo(g.w)); v[7] *= sigmoidf_(bf_hi(g.w)); }
;                     u32x4 w; w.x = pkh(v[0], v[1]); w.y = pkh(v[2], v[3]); w.z = pkh(v[4], v[5]); w.w = pkh(v[6], v[7]);
;                     *(u32x4*)(ob + (size_t)row * LDC + col) = w; }
	v_max_f32_e32 v141, 0, v0
	v_cvt_pk_bf16_f32 v134, v134, v135
	v_cvt_pk_bf16_f32 v135, v136, v137
	v_cvt_pk_bf16_f32 v136, v138, v139
	v_lshlrev_b64 v[138:139], 14, v[142:143]
	v_pk_mul_f32 v[140:141], v[140:141], v[140:141]
	v_lshl_add_u64 v[138:139], s[10:11], 0, v[138:139]
	v_cvt_pk_bf16_f32 v137, v140, v141
	v_lshl_add_u64 v[138:139], v[138:139], 0, v[132:133]
	v_max_f32_e32 v0, v52, v52
	global_store_dwordx4 v[138:139], v[134:137], off nt
	s_nop 1
	v_max_f32_e32 v134, 0, v0
	v_max_f32_e32 v0, v53, v53
	v_max_f32_e32 v135, 0, v0
	v_max_f32_e32 v0, v54, v54
	v_max_f32_e32 v136, 0, v0
	v_max_f32_e32 v0, v55, v55
	v_max_f32_e32 v137, 0, v0
	v_max_f32_e32 v0, v56, v56
	v_max_f32_e32 v140, 0, v0
	v_max_f32_e32 v0, v57, v57
	v_max_f32_e32 v141, 0, v0
	v_max_f32_e32 v0, v58, v58
	v_max_f32_e32 v142, 0, v0
	v_max_f32_e32 v0, v59, v59
	v_max_f32_e32 v143, 0, v0
	v_pk_mul_f32 v[134:135], v[134:135], v[134:135]
	v_pk_mul_f32 v[136:137], v[136:137], v[136:137]
	v_pk_mul_f32 v[140:141], v[140:141], v[140:141]
	v_pk_mul_f32 v[142:143], v[142:143], v[142:143]
	v_cvt_pk_bf16_f32 v134, v134, v135
	v_cvt_pk_bf16_f32 v135, v136, v137
	v_cvt_pk_bf16_f32 v136, v140, v141
	v_cvt_pk_bf16_f32 v137, v142, v143
	v_max_f32_e32 v0, v20, v20
	global_store_dwordx4 v[138:139], v[134:137], off offset:256 nt
	v_add_u32_e32 v142, 0xa0, v2
	v_ashrrev_i32_e32 v143, 31, v142
	v_max_f32_e32 v134, 0, v0
	v_max_f32_e32 v0, v21, v21
	v_max_f32_e32 v135, 0, v0
	v_max_f32_e32 v0, v22, v22
	v_max_f32_e32 v136, 0, v0
	v_max_f32_e32 v0, v23, v23
	v_max_f32_e32 v137, 0, v0
	v_max_f32_e32 v0, v24, v24
	v_max_f32_e32 v138, 0, v0
	v_max_f32_e32 v0, v25, v25
	v_max_f32_e32 v139, 0, v0
	v_max_f32_e32 v0, v26, v26
	v_pk_mul_f32 v[134:135], v[134:135], v[134:135]
	v_pk_mul_f32 v[136:137], v[136:137], v[136:137]
	v_pk_mul_f32 v[138:139], v[138:139], v[138:139]
	v_max_f32_e32 v140, 0, v0
	v_max_f32_e32 v0, v27, v27
	v_max_f32_e32 v141, 0, v0
	v_cvt_pk_bf16_f32 v134, v134, v135
	v_cvt_pk_bf16_f32 v135, v136, v137
	v_cvt_pk_bf16_f32 v136, v138, v139
	v_lshlrev_b64 v[138:139], 14, v[142:143]
	v_pk_mul_f32 v[140:141], v[140:141], v[140:141]
	v_lshl_add_u64 v[138:139], s[10:11], 0, v[138:139]
	v_cvt_pk_bf16_f32 v137, v140, v141
	v_lshl_add_u64 v[138:139], v[138:139], 0, v[132:133]
	v_max_f32_e32 v0, v28, v28
	global_store_dwordx4 v[138:139], v[134:137], off nt
	v_add_u32_e32 v2, 0xb0, v2
	v_ashrrev_i32_e32 v3, 31, v2
	v_max_f32_e32 v134, 0, v0
	v_max_f32_e32 v0, v29, v29
	v_max_f32_e32 v135, 0, v0
	v_max_f32_e32 v0, v30, v30
	v_max_f32_e32 v136, 0, v0
	v_max_f32_e32 v0, v31, v31
	v_max_f32_e32 v137, 0, v0
	v_max_f32_e32 v0, v32, v32
	v_max_f32_e32 v140, 0, v0
	v_max_f32_e32 v0, v33, v33
	v_max_f32_e32 v141, 0, v0
	v_max_f32_e32 v0, v34, v34
	v_max_f32_e32 v142, 0, v0
	v_max_f32_e32 v0, v35, v35
	v_max_f32_e32 v143, 0, v0
	v_pk_mul_f32 v[134:135], v[134:135], v[134:135]
	v_pk_mul_f32 v[136:137], v[136:137], v[136:137]
	v_pk_mul_f32 v[140:141], v[140:141], v[140:141]
	v_pk_mul_f32 v[142:143], v[142:143], v[142:143]
	v_cvt_pk_bf16_f32 v134, v134, v135
	v_cvt_pk_bf16_f32 v135, v136, v137
	v_cvt_pk_bf16_f32 v136, v140, v141
	v_cvt_pk_bf16_f32 v137, v142, v143
	v_max_f32_e32 v0, v4, v4
	global_store_dwordx4 v[138:139], v[134:137], off offset:256 nt
	v_lshlrev_b64 v[2:3], 14, v[2:3]
	v_lshl_add_u64 v[2:3], s[10:11], 0, v[2:3]
	v_max_f32_e32 v134, 0, v0
	v_max_f32_e32 v0, v5, v5
	v_max_f32_e32 v135, 0, v0
	v_max_f32_e32 v0, v6, v6
	v_max_f32_e32 v136, 0, v0
	v_max_f32_e32 v0, v7, v7
	v_max_f32_e32 v137, 0, v0
	v_max_f32_e32 v0, v8, v8
	v_max_f32_e32 v138, 0, v0
	v_max_f32_e32 v0, v9, v9
	v_max_f32_e32 v139, 0, v0
	v_max_f32_e32 v0, v10, v10
	v_max_f32_e32 v140, 0, v0
	v_max_f32_e32 v0, v11, v11
	v_max_f32_e32 v141, 0, v0
	v_max_f32_e32 v0, v12, v12
	v_pk_mul_f32 v[134:135], v[134:135], v[134:135]
	v_pk_mul_f32 v[136:137], v[136:137], v[136:137]
	v_pk_mul_f32 v[138:139], v[138:139], v[138:139]
	v_pk_mul_f32 v[140:141], v[140:141], v[140:141]
	v_lshl_add_u64 v[2:3], v[2:3], 0, v[132:133]
	v_max_f32_e32 v132, 0, v0
	v_max_f32_e32 v0, v13, v13
	v_cvt_pk_bf16_f32 v134, v134, v135
	v_cvt_pk_bf16_f32 v135, v136, v137
	v_cvt_pk_bf16_f32 v136, v138, v139
	v_cvt_pk_bf16_f32 v137, v140, v141
	v_max_f32_e32 v133, 0, v0
	v_max_f32_e32 v0, v14, v14
	global_store_dwordx4 v[2:3], v[134:137], off nt
	v_pk_mul_f32 v[132:133], v[132:133], v[132:133]
	s_nop 0
	v_max_f32_e32 v134, 0, v0
	v_max_f32_e32 v0, v15, v15
	v_max_f32_e32 v135, 0, v0
	v_max_f32_e32 v0, v16, v16
	v_max_f32_e32 v136, 0, v0
	v_max_f32_e32 v0, v17, v17
	v_max_f32_e32 v137, 0, v0
	v_max_f32_e32 v0, v18, v18
	v_max_f32_e32 v138, 0, v0
	v_max_f32_e32 v0, v19, v19
	v_max_f32_e32 v139, 0, v0
	v_pk_mul_f32 v[134:135], v[134:135], v[134:135]
	v_pk_mul_f32 v[136:137], v[136:137], v[136:137]
	v_pk_mul_f32 v[138:139], v[138:139], v[138:139]
	v_cvt_pk_bf16_f32 v132, v132, v133
	v_cvt_pk_bf16_f32 v133, v134, v135
	v_cvt_pk_bf16_f32 v134, v136, v137
	v_cvt_pk_bf16_f32 v135, v138, v139
	global_store_dwordx4 v[2:3], v[132:135], off offset:256 nt

; __device__ __forceinline__ unsigned pkh(float lo, float hi) { f32v2_t v; v.x = lo; v.y = hi; return __builtin_bit_cast(unsigned, __builtin_convertvector(v, bf16v2_t)); }
; __device__ __forceinline__ float bf_lo(unsigned w) { return __uint_as_float(w << 16); }
; __device__ __forceinline__ float bf_hi(unsigned w) { return __uint_as_float(w & 0xffff0000u); }
; __device__ __forceinline__ float sigmoidf_(float x) { return 1.0f / (1.0f + __expf(-x)); }
;     template <int MODE> __device__ __forceinline__ void run(const pg8::f32x4 (&acc)[2][2][4][2], const pg8::Unit& u, int wr, int wc, int fr, int fq) const {
;     ...
;                 for (int q = 0; q < 4; ++q) { const int m = 2 * mp + (q >> 1), bj = q & 1; const int row = u.pm * 256 + ai * 128 + wr * 64 + m * 16 + fr, col = u.pn * 256 + bj * 128 + wc * 32 + 8 * fq;
;                     const pg8::f32x4 t0 = acc[ai][bj][m][0], t1 = acc[ai][bj][m][1];
;                     float v[8] = {t0[0], t0[1], t0[2], t0[3], t1[0], t1[1], t1[2], t1[3]};
;                     if constexpr (MODE == 5) {
; #pragma unroll
;                         for (int e = 0; e < 8; ++e) { const float r = fmaxf(v[e], 0.f); v[e] = r * r; }
;                     }
;                     if constexpr (MODE == 6) { const u32x4 g = gpre[q];
;                         v[0] *= sigmoidf_(bf_lo(g.x)); v[1] *= sigmoidf_(bf_hi(g.x)); v[2] *= sigmoidf_(bf_lo(g.y)); v[3] *= sigmoidf_(bf_hi(g.y));
;                         v[4] *= sigmoidf_(bf_lo(g.z)); v[5] *= sigmoidf_(bf_hi(g.z)); v[6] *= sigmoidf_(bf_lo(g.w)); v[7] *= sigmoidf_(bf_hi(g.w)); }
;                     u32x4 w; w.x = pkh(v[0], v[1]); w.y = pkh(v[2], v[3]); w.z = pkh(v[4], v[5]); w.w = pkh(v[6], v[7]);
;                     *(u32x4*)(ob + (size_t)row * LDC + col) = w; }
;                 asm volatile("" ::: "memory"); }
.LBB0_74:
	v_mov_b32_e32 v0, v210
	s_lshl_b32 s2, s53, 8
	v_and_or_b32 v2, v0, 15, s49
	v_lshrrev_b32_e32 v0, 1, v0
	v_and_or_b32 v0, v0, 24, s2
	v_lshl_add_u32 v134, s54, 8, v2
	v_or_b32_e32 v2, s50, v0
	v_cvt_pk_bf16_f32 v116, v116, v117
	v_cvt_pk_bf16_f32 v117, v118, v119
	v_cvt_pk_bf16_f32 v118, v120, v121
	v_mov_b64_e32 v[120:121], s[10:11]
	v_ashrrev_i32_e32 v3, 31, v2
	v_cvt_pk_bf16_f32 v119, v122, v123
	v_mad_i64_i32 v[122:123], s[28:29], v134, s76, v[120:121]
	v_lshlrev_b64 v[132:133], 1, v[2:3]
	v_lshl_add_u64 v[2:3], v[122:123], 0, v[132:133]
	global_store_dwordx4 v[2:3], v[116:119], off nt
	v_or_b32_e32 v0, 16, v134
	v_cvt_pk_bf16_f32 v100, v100, v101
	v_cvt_pk_bf16_f32 v116, v124, v125
	v_cvt_pk_bf16_f32 v117, v126, v127
	v_cvt_pk_bf16_f32 v118, v128, v129
	v_cvt_pk_bf16_f32 v119, v130, v131
	global_store_dwordx4 v[2:3], v[116:119], off offset:256 nt
	v_mad_i64_i32 v[2:3], s[28:29], v0, s76, v[120:121]
	v_cvt_pk_bf16_f32 v101, v102, v103
	v_cvt_pk_bf16_f32 v102, v104, v105
	v_cvt_pk_bf16_f32 v103, v106, v107
	v_lshl_add_u64 v[2:3], v[2:3], 0, v[132:133]
	global_store_dwordx4 v[2:3], v[100:103], off nt
	v_or_b32_e32 v0, 32, v134
	v_cvt_pk_bf16_f32 v76, v76, v77
	v_cvt_pk_bf16_f32 v100, v108, v109
	v_cvt_pk_bf16_f32 v101, v110, v111
	v_cvt_pk_bf16_f32 v102, v112, v113
	v_cvt_pk_bf16_f32 v103, v114, v115
	global_store_dwordx4 v[2:3], v[100:103], off offset:256 nt
	v_mad_i64_i32 v[2:3], s[28:29], v0, s76, v[120:121]
	v_cvt_pk_bf16_f32 v77, v78, v79
	v_cvt_pk_bf16_f32 v78, v80, v81
	v_cvt_pk_bf16_f32 v79, v82, v83
	v_lshl_add_u64 v[2:3], v[2:3], 0, v[132:133]
	global_store_dwordx4 v[2:3], v[76:79], off nt
	v_or_b32_e32 v0, 48, v134
	v_cvt_pk_bf16_f32 v44, v44, v45
	v_cvt_pk_bf16_f32 v76, v92, v93
	v_cvt_pk_bf16_f32 v77, v94, v95
	v_cvt_pk_bf16_f32 v78, v96, v97
	v_cvt_pk_bf16_f32 v79, v98, v99
	global_store_dwordx4 v[2:3], v[76:79], off offset:256 nt
	v_mad_i64_i32 v[2:3], s[28:29], v0, s76, v[120:121]
	v_cvt_pk_bf16_f32 v45, v46, v47
	v_cvt_pk_bf16_f32 v46, v48, v49
	v_cvt_pk_bf16_f32 v47, v50, v51
	v_lshl_add_u64 v[2:3], v[2:3], 0, v[132:133]
	global_store_dwordx4 v[2:3], v[44:47], off nt
	v_add_u32_e32 v0, 0x80, v134
	v_cvt_pk_bf16_f32 v36, v36, v37
	v_cvt_pk_bf16_f32 v44, v68, v69
	v_cvt_pk_bf16_f32 v45, v70, v71
	v_cvt_pk_bf16_f32 v46, v72, v73
	v_cvt_pk_bf16_f32 v47, v74, v75
	global_store_dwordx4 v[2:3], v[44:47], off offset:256 nt
	v_mad_i64_i32 v[2:3], s[28:29], v0, s76, v[120:121]
	s_nop 0
	v_cvt_pk_bf16_f32 v44, v60, v61
	v_cvt_pk_bf16_f32 v45, v62, v63
	v_cvt_pk_bf16_f32 v46, v64, v65
	v_cvt_pk_bf16_f32 v47, v66, v67
	v_lshl_add_u64 v[2:3], v[2:3], 0, v[132:133]
	global_store_dwordx4 v[2:3], v[44:47], off nt
	v_add_u32_e32 v0, 0x90, v134
	v_cvt_pk_bf16_f32 v37, v38, v39
	v_cvt_pk_bf16_f32 v44, v84, v85
	v_cvt_pk_bf16_f32 v45, v86, v87
	v_cvt_pk_bf16_f32 v46, v88, v89
	v_cvt_pk_bf16_f32 v47, v90, v91
	global_store_dwordx4 v[2:3], v[44:47], off offset:256 nt
	v_mad_i64_i32 v[2:3], s[28:29], v0, s76, v[120:121]
	v_cvt_pk_bf16_f32 v38, v40, v41
	v_cvt_pk_bf16_f32 v39, v42, v43
	v_lshl_add_u64 v[2:3], v[2:3], 0, v[132:133]
	global_store_dwordx4 v[2:3], v[36:39], off nt
	v_add_u32_e32 v0, 0xa0, v134
	v_cvt_pk_bf16_f32 v20, v20, v21
	v_cvt_pk_bf16_f32 v36, v52, v53
	v_cvt_pk_bf16_f32 v37, v54, v55
	v_cvt_pk_bf16_f32 v38, v56, v57
	v_cvt_pk_bf16_f32 v39, v58, v59
	global_store_dwordx4 v[2:3], v[36:39], off offset:256 nt
	v_mad_i64_i32 v[2:3], s[28:29], v0, s76, v[120:121]
	v_cvt_pk_bf16_f32 v21, v22, v23
	v_cvt_pk_bf16_f32 v22, v24, v25
	v_cvt_pk_bf16_f32 v23, v26, v27
	v_lshl_add_u64 v[2:3], v[2:3], 0, v[132:133]
	global_store_dwordx4 v[2:3], v[20:23], off nt
	v_add_u32_e32 v0, 0xb0, v134
	s_nop 0
	v_cvt_pk_bf16_f32 v20, v28, v29
	v_cvt_pk_bf16_f32 v21, v30, v31
	v_cvt_pk_bf16_f32 v22, v32, v33
	v_cvt_pk_bf16_f32 v23, v34, v35
	global_store_dwordx4 v[2:3], v[20:23], off offset:256 nt
	v_cvt_pk_bf16_f32 v3, v6, v7
	v_mad_i64_i32 v[6:7], s[28:29], v0, s76, v[120:121]
	v_cvt_pk_bf16_f32 v2, v4, v5
	v_cvt_pk_bf16_f32 v4, v8, v9
	v_cvt_pk_bf16_f32 v5, v10, v11
	v_lshl_add_u64 v[6:7], v[6:7], 0, v[132:133]
	global_store_dwordx4 v[6:7], v[2:5], off nt
	s_nop 1
	v_cvt_pk_bf16_f32 v2, v12, v13
	v_cvt_pk_bf16_f32 v3, v14, v15
	v_cvt_pk_bf16_f32 v4, v16, v17
	v_cvt_pk_bf16_f32 v5, v18, v19
	global_store_dwordx4 v[6:7], v[2:5], off offset:256 nt
	s_and_b64 vcc, exec, s[4:5]
	s_mov_b64 s[4:5], -1
	s_cbranch_vccnz .LBB0_45
